# gemm_in prompt tiles (512 = 2 per block) on the 256x256 8-phase core with routed epilogue; 16 sample-row tiles still on the original code via a range stub
# baseline (speedup 1.0000x reference)
; DI void gemm_in(const Params& p, int l, int bid, int nb, char* smem, const int tid) {
;     const bf16_t* A = (const bf16_t*)(p.ws + B_XN);
;     const bf16_t* Bt = (const bf16_t*)(p.ws + W_IN);
;     const int ntn = 16, ntiles = 130 * ntn;
;     const int lane = tid & 63, wave = __builtin_amdgcn_readfirstlane(tid >> 6), wm = wave >> 1, wn = wave & 1, r = lane & 15, q = lane >> 4;
;     TileIter ti; ti.init(65, ntn, bid, nb);
;     int tm, tn, tm2 = 0, tn2 = 0;
;     bool have = ti.next(tm, tn);
;     Ring rg; rg.st = 0; rg.primed = 0;
;     for (; have; tm = tm2, tn = tn2) {
;         have = ti.next(tm2, tn2);
;         const int m0 = tm * 256, n0 = tn * 128;
;         f32x4 acc[4][4]; zero_acc(acc);
;         gemm_stream(A, 1024, Bt, 1024, 1024, m0, n0, have, tm2 * 256, tn2 * 128, smem, acc, tid, rg);
.LBB0_659:
	s_and_b64 vcc, exec, s[0:1]
	s_cbranch_vccz .LBB0_701
	s_branch .Lin_entry
	v_readlane_b32 s0, v240, 53
	v_readlane_b32 s1, v240, 54
	s_andn2_b64 vcc, exec, s[0:1]
	v_readlane_b32 s0, v231, 0
	v_readlane_b32 s1, v231, 1
	s_mov_b32 s3, s0
	v_readlane_b32 s0, v238, 54
	v_readfirstlane_b32 s33, v227
	s_movk_i32 s2, 0x410
	s_mov_b32 s10, s0
	v_readlane_b32 s1, v238, 55
	s_cbranch_vccz .LBB0_663
.Lin_old661:
	s_cmp_lt_i32 s3, s2
	s_cselect_b64 s[0:1], -1, 0
	s_cmp_ge_i32 s3, s2
	s_cbranch_scc1 .LBB0_664

;     DI void init(int ntm_, int ntn_, int bid, int nb) {
;         ntm = ntm_; ntn = ntn_;
;         const int nt = ntm * ntn;
;         if ((nb & 7) == 0) { const int x = bid & 7, per = (nt + 7) >> 3; L = x * per + (bid >> 3); end = min((x + 1) * per, nt); step = nb >> 3; }
;         else { L = bid; end = nt; step = nb; }
;     }
; DI void gemm_in(const Params& p, int l, int bid, int nb, char* smem, const int tid) {
;     const bf16_t* A = (const bf16_t*)(p.ws + B_XN);
;     const bf16_t* Bt = (const bf16_t*)(p.ws + W_IN);
;     const int ntn = 16, ntiles = 130 * ntn;
;     const int lane = tid & 63, wave = __builtin_amdgcn_readfirstlane(tid >> 6), wm = wave >> 1, wn = wave & 1, r = lane & 15, q = lane >> 4;
;     TileIter ti; ti.init(65, ntn, bid, nb);
;     int tm, tn, tm2 = 0, tn2 = 0;
;     bool have = ti.next(tm, tn);
;     Ring rg; rg.st = 0; rg.primed = 0;
;     for (; have; tm = tm2, tn = tn2) {
;         have = ti.next(tm2, tn2);
;         const int m0 = tm * 256, n0 = tn * 128;
;         f32x4 acc[4][4]; zero_acc(acc);
;         gemm_stream(A, 1024, Bt, 1024, 1024, m0, n0, have, tm2 * 256, tn2 * 128, smem, acc, tid, rg);
.Lin_entry:
	s_mov_b32 s61, 0x1080000
	v_readlane_b32 s51, v240, 0
	v_readlane_b32 s53, v238, 54
	v_readfirstlane_b32 s10, v193
	s_nop 3
	s_lshr_b32 s10, s10, 6
	s_lshr_b32 s33, s10, 2
	s_and_b32 s36, s10, 3
	s_lshl_b32 s39, s10, 11
	s_add_i32 s39, s39, 16
	s_and_b32 s1, s53, 7
	s_cmp_eq_u32 s1, 0
	s_cbranch_scc0 .Lin_simple
	s_and_b32 s1, s51, 7
	s_lshr_b32 s2, s51, 3
	s_lshl_b32 s3, s1, 6
	s_add_i32 s51, s3, s2
	s_add_i32 s52, s3, 64
	s_lshr_b32 s53, s53, 3
	s_branch .Lin_ranged
.Lin_simple:
	s_movk_i32 s52, 0x200
.Lin_ranged:
	s_cmp_ge_u32 s51, s52
	s_cbranch_scc1 .Lin_stub
	v_and_b32_e32 v190, 63, v193
	v_and_b32_e32 v191, 15, v190
	v_lshrrev_b32_e32 v17, 4, v190
	v_lshrrev_b32_e32 v18, 3, v190
	v_and_b32_e32 v19, 7, v190
	v_xor_b32_e32 v195, v19, v17
	v_lshlrev_b32_e32 v195, 4, v195
	v_lshl_add_u32 v184, v18, 11, v195
	v_or_b32_e32 v195, 4, v17
	v_xor_b32_e32 v195, v19, v195
	v_lshlrev_b32_e32 v195, 4, v195
	v_add_u32_e32 v227, 8, v18
	v_lshl_add_u32 v185, v227, 11, v195
	v_lshrrev_b32_e32 v195, 1, v191
	v_xor_b32_e32 v195, v17, v195
	v_lshlrev_b32_e32 v195, 4, v195
	s_lshl_b32 s1, s33, 6
	v_add_u32_e32 v230, s1, v191
	v_lshl_add_u32 v186, v230, 7, v195
	v_xor_b32_e32 v187, 64, v186
	s_lshl_b32 s1, s36, 5
	v_add_u32_e32 v227, s1, v191
	v_lshl_add_u32 v188, v227, 7, v195
	v_add_u32_e32 v188, 0x10000, v188
	v_xor_b32_e32 v189, 64, v188
	s_lshl_b32 s1, s36, 7
	v_lshl_add_u32 v236, v17, 4, s1
	v_lshrrev_b32_e32 v228, 1, v236
	v_lshl_add_u32 v237, v230, 9, v228
	s_lshr_b32 s1, s51, 6
	s_and_b32 s2, s51, 63
	s_lshr_b32 s58, s2, 3
	s_and_b32 s2, s2, 7
	s_lshl_b32 s1, s1, 3
	s_add_i32 s57, s1, s2
	s_lshl_b32 s1, s57, 19
	s_lshl_b32 s2, s10, 15
	s_add_u32 s1, s1, s2
	s_add_u32 s1, s1, 0x3240000
	s_add_u32 s66, s88, s1
	s_addc_u32 s67, s89, 0
	s_add_u32 s68, s66, 0x40000
	s_addc_u32 s69, s67, 0
	s_lshl_b32 s1, s58, 19
	s_add_u32 s1, s1, s2
	s_add_u32 s1, s1, s61
	s_add_u32 s70, s88, s1
	s_addc_u32 s71, s89, 0
	s_add_u32 s72, s70, 0x40000
	s_addc_u32 s73, s71, 0
	s_add_i32 m0, s39, 0x10000
	s_nop 0
	global_load_lds_dwordx4 v184, s[70:71]
	s_add_i32 m0, s39, 0x10400
	s_nop 0
	global_load_lds_dwordx4 v185, s[70:71]
	s_add_u32 s70, s70, 0x80
	s_addc_u32 s71, s71, 0
	s_add_i32 m0, s39, 0x0
	s_nop 0
	global_load_lds_dwordx4 v184, s[66:67]
	s_add_i32 m0, s39, 0x400
	s_nop 0
	global_load_lds_dwordx4 v185, s[66:67]
	s_add_u32 s66, s66, 0x80
	s_addc_u32 s67, s67, 0
	s_add_i32 m0, s39, 0x14000
	s_nop 0
	global_load_lds_dwordx4 v184, s[72:73]
	s_add_i32 m0, s39, 0x14400
	s_nop 0
	global_load_lds_dwordx4 v185, s[72:73]
	s_add_u32 s72, s72, 0x80
	s_addc_u32 s73, s73, 0
	s_add_i32 m0, s39, 0x4000
	s_nop 0
	global_load_lds_dwordx4 v184, s[68:69]
	s_add_i32 m0, s39, 0x4400
	s_nop 0
	global_load_lds_dwordx4 v185, s[68:69]
	s_add_u32 s68, s68, 0x80
	s_addc_u32 s69, s69, 0
	s_cmp_eq_u32 s33, 0
	s_cbranch_scc1 .Lin_lead
	s_barrier

;     DI bool next(int& tm, int& tn) {
;         if (L >= end) return false;
;         const int gsz = 8 * ntn, grp = L / gsz, rem = L - grp * gsz, rows = min(8, ntm - grp * 8);
;         tn = rem / rows; tm = grp * 8 + (rem - tn * rows);
;         L += step; return true;
;     }
; DI void gemm_in(const Params& p, int l, int bid, int nb, char* smem, const int tid) {
;     ...
;     for (; have; tm = tm2, tn = tn2) {
;         have = ti.next(tm2, tn2);
;         const int m0 = tm * 256, n0 = tn * 128;
;         f32x4 acc[4][4]; zero_acc(acc);
;         gemm_stream(A, 1024, Bt, 1024, 1024, m0, n0, have, tm2 * 256, tn2 * 128, smem, acc, tid, rg);
.Lin_tile:
	s_add_u32 s76, s51, s53
	s_cmp_lt_u32 s76, s52
	s_cselect_b32 s54, 1, 0
	s_cbranch_scc0 .Lin_nonext
	s_lshr_b32 s1, s76, 6
	s_and_b32 s2, s76, 63
	s_lshr_b32 s60, s2, 3
	s_and_b32 s2, s2, 7
	s_lshl_b32 s1, s1, 3
	s_add_i32 s59, s1, s2
	s_lshl_b32 s1, s59, 19
	s_lshl_b32 s2, s10, 15
	s_add_u32 s1, s1, s2
	s_add_u32 s1, s1, 0x3240000
	s_add_u32 s74, s88, s1
	s_addc_u32 s75, s89, 0
	s_add_u32 s78, s74, 0x40000
	s_addc_u32 s79, s75, 0
	s_lshl_b32 s1, s60, 19
	s_add_u32 s1, s1, s2
	s_add_u32 s1, s1, s61
	s_add_u32 s80, s88, s1
	s_addc_u32 s81, s89, 0
	s_add_u32 s82, s80, 0x40000
	s_addc_u32 s83, s81, 0

; DI unsigned pk2(float lo, float hi) { const f32x2 v = {lo, hi}; return __builtin_bit_cast(unsigned, __builtin_convertvector(v, bf2_t)); }
; DI void gemm_in(const Params& p, int l, int bid, int nb, char* smem, const int tid) {
;     ...
;         const int nb0 = n0 + wn * 64;
;         const int seg = nb0 >> 8;
;         const int cin = nb0 & 255;
;         if (seg == 0 || seg == 3) {
;             bf16_t* Q = (bf16_t*)(p.ws + (seg == 0 ? B_QA : B_QC));
; #pragma unroll
;             for (int mi = 0; mi < 4; ++mi) {
;                 const int row = m0 + wm * 64 + mi * 16 + r;
; #pragma unroll
;                 for (int ni = 0; ni < 4; ++ni) {
;                     u32x2 w; w.x = pk2(acc[mi][ni][0], acc[mi][ni][1]); w.y = pk2(acc[mi][ni][2], acc[mi][ni][3]);
;                     *(u32x2*)(Q + (size_t)row * 256 + cin + ni * 16 + q * 4) = w;
;                 }
;             }
;         } else if (seg < 6) {
;             const size_t boff = seg == 1 ? B_KA : seg == 2 ? B_VA : seg == 4 ? B_KC : B_VC;
;             const bool samp = m0 >= NP;
;             const size_t ooff = samp ? (seg == 1 ? O_AKS : seg == 2 ? O_AVS : seg == 4 ? O_CKS : O_CVS) : (seg == 1 ? O_AKP : seg == 2 ? O_AVP : seg == 4 ? O_CKP : O_CVP);
;             bf16_t* KV = (bf16_t*)(p.ws + boff);
; #pragma unroll
;             for (int mi = 0; mi < 4; ++mi) {
;                 const int row = m0 + wm * 64 + mi * 16 + r;
;                 const size_t srow = samp ? (size_t)(l * NS + (row - NP)) : (size_t)(l * NP + row);
;                 const size_t kr = (size_t)krow_of(row);
; #pragma unroll
;                 for (int ni = 0; ni < 4; ++ni) {
;                     const int c = cin + ni * 16 + q * 4;
;                     *(f32x4*)(p.out + ooff + srow * 256 + c) = acc[mi][ni];
;                     u32x2 w; w.x = pk2(acc[mi][ni][0], acc[mi][ni][1]); w.y = pk2(acc[mi][ni][2], acc[mi][ni][3]);
;                     *(u32x2*)(KV + kr * 256 + c) = w;
;                 }
;             }
.Lin_epi:
	s_nop 7
	s_nop 7
	s_cmp_eq_u32 s58, 0
	s_cbranch_scc1 .Lin_q1
	s_cmp_eq_u32 s58, 3
	s_cbranch_scc1 .Lin_q1
	s_cmp_ge_u32 s58, 6
	s_cbranch_scc1 .Lin_sm1
	s_mov_b32 s1, 0xb500000
	s_mov_b32 s62, 0x9fc0000
	s_cmp_eq_u32 s58, 4
	s_cselect_b32 s1, 0x9500000, s1
	s_cselect_b32 s62, 0x93a0000, s62
	s_cmp_eq_u32 s58, 2
	s_cselect_b32 s1, 0x6100000, s1
	s_cselect_b32 s62, 0x8780000, s62
	s_cmp_eq_u32 s58, 1
	s_cselect_b32 s1, 0x4100000, s1
	s_cselect_b32 s62, 0x7b60000, s62
	v_readlane_b32 s37, v231, 4
	s_lshl_b32 s37, s37, 24
	s_add_u32 s1, s1, s37
	s_lshl_b32 s37, s57, 18
	s_add_u32 s1, s1, s37
	v_readlane_b32 s2, v240, 5
	v_readlane_b32 s3, v240, 6
	s_nop 3
	s_add_u32 s2, s2, s1
	s_addc_u32 s3, s3, 0
	s_lshl_b32 s37, s57, 17
	s_add_u32 s62, s62, s37
	s_add_u32 s96, s88, s62
	s_addc_u32 s97, s89, 0
	v_lshlrev_b32_e32 v168, 1, v237
	global_store_dwordx4 v168, v[24:27], s[2:3] offset:0
	global_store_dwordx4 v168, v[28:31], s[2:3] offset:64
	global_store_dwordx4 v168, v[56:59], s[2:3] offset:512
	global_store_dwordx4 v168, v[60:63], s[2:3] offset:576
	v_cvt_pk_bf16_f32 v152, v24, v25
	v_cvt_pk_bf16_f32 v153, v26, v27
	global_store_dwordx2 v237, v[152:153], s[96:97] offset:0
	v_cvt_pk_bf16_f32 v154, v28, v29
	v_cvt_pk_bf16_f32 v155, v30, v31
	global_store_dwordx2 v237, v[154:155], s[96:97] offset:32
	v_cvt_pk_bf16_f32 v156, v56, v57
	v_cvt_pk_bf16_f32 v157, v58, v59
	global_store_dwordx2 v237, v[156:157], s[96:97] offset:256
	v_cvt_pk_bf16_f32 v158, v60, v61
	v_cvt_pk_bf16_f32 v159, v62, v63
	global_store_dwordx2 v237, v[158:159], s[96:97] offset:288
	s_add_u32 s2, s2, 0x4000
	s_addc_u32 s3, s3, 0
	s_add_u32 s96, s96, 0x2000
	s_addc_u32 s97, s97, 0
	global_store_dwordx4 v168, v[32:35], s[2:3] offset:0
	global_store_dwordx4 v168, v[36:39], s[2:3] offset:64
	global_store_dwordx4 v168, v[64:67], s[2:3] offset:512
	global_store_dwordx4 v168, v[68:71], s[2:3] offset:576
	v_cvt_pk_bf16_f32 v160, v32, v33
	v_cvt_pk_bf16_f32 v161, v34, v35
	global_store_dwordx2 v237, v[160:161], s[96:97] offset:0
	v_cvt_pk_bf16_f32 v162, v36, v37
	v_cvt_pk_bf16_f32 v163, v38, v39
	global_store_dwordx2 v237, v[162:163], s[96:97] offset:32
	v_cvt_pk_bf16_f32 v164, v64, v65
	v_cvt_pk_bf16_f32 v165, v66, v67
	global_store_dwordx2 v237, v[164:165], s[96:97] offset:256
	v_cvt_pk_bf16_f32 v166, v68, v69
	v_cvt_pk_bf16_f32 v167, v70, v71
	global_store_dwordx2 v237, v[166:167], s[96:97] offset:288
	s_add_u32 s2, s2, 0x4000
	s_addc_u32 s3, s3, 0
	s_add_u32 s96, s96, 0x2000
	s_addc_u32 s97, s97, 0
	global_store_dwordx4 v168, v[40:43], s[2:3] offset:0
	global_store_dwordx4 v168, v[44:47], s[2:3] offset:64
	global_store_dwordx4 v168, v[72:75], s[2:3] offset:512
	global_store_dwordx4 v168, v[76:79], s[2:3] offset:576
	v_cvt_pk_bf16_f32 v152, v40, v41
	v_cvt_pk_bf16_f32 v153, v42, v43
	global_store_dwordx2 v237, v[152:153], s[96:97] offset:0
	v_cvt_pk_bf16_f32 v154, v44, v45
	v_cvt_pk_bf16_f32 v155, v46, v47
	global_store_dwordx2 v237, v[154:155], s[96:97] offset:32
	v_cvt_pk_bf16_f32 v156, v72, v73
	v_cvt_pk_bf16_f32 v157, v74, v75
	global_store_dwordx2 v237, v[156:157], s[96:97] offset:256
	v_cvt_pk_bf16_f32 v158, v76, v77
	v_cvt_pk_bf16_f32 v159, v78, v79
	global_store_dwordx2 v237, v[158:159], s[96:97] offset:288
	s_add_u32 s2, s2, 0x4000
	s_addc_u32 s3, s3, 0
	s_add_u32 s96, s96, 0x2000
	s_addc_u32 s97, s97, 0
	global_store_dwordx4 v168, v[48:51], s[2:3] offset:0
	global_store_dwordx4 v168, v[52:55], s[2:3] offset:64
	global_store_dwordx4 v168, v[80:83], s[2:3] offset:512
	global_store_dwordx4 v168, v[84:87], s[2:3] offset:576
	v_cvt_pk_bf16_f32 v160, v48, v49
	v_cvt_pk_bf16_f32 v161, v50, v51
	global_store_dwordx2 v237, v[160:161], s[96:97] offset:0
	v_cvt_pk_bf16_f32 v162, v52, v53
	v_cvt_pk_bf16_f32 v163, v54, v55
	global_store_dwordx2 v237, v[162:163], s[96:97] offset:32
	v_cvt_pk_bf16_f32 v164, v80, v81
	v_cvt_pk_bf16_f32 v165, v82, v83
	global_store_dwordx2 v237, v[164:165], s[96:97] offset:256
	v_cvt_pk_bf16_f32 v166, v84, v85
	v_cvt_pk_bf16_f32 v167, v86, v87
	global_store_dwordx2 v237, v[166:167], s[96:97] offset:288
	s_add_u32 s2, s2, 0x14000
	s_addc_u32 s3, s3, 0
	s_add_u32 s96, s96, 0xa000
	s_addc_u32 s97, s97, 0
	global_store_dwordx4 v168, v[88:91], s[2:3] offset:0
	global_store_dwordx4 v168, v[92:95], s[2:3] offset:64
	global_store_dwordx4 v168, v[120:123], s[2:3] offset:512
	global_store_dwordx4 v168, v[124:127], s[2:3] offset:576
	v_cvt_pk_bf16_f32 v152, v88, v89
	v_cvt_pk_bf16_f32 v153, v90, v91
	global_store_dwordx2 v237, v[152:153], s[96:97] offset:0
	v_cvt_pk_bf16_f32 v154, v92, v93
	v_cvt_pk_bf16_f32 v155, v94, v95
	global_store_dwordx2 v237, v[154:155], s[96:97] offset:32
	v_cvt_pk_bf16_f32 v156, v120, v121
	v_cvt_pk_bf16_f32 v157, v122, v123
	global_store_dwordx2 v237, v[156:157], s[96:97] offset:256
	v_cvt_pk_bf16_f32 v158, v124, v125
	v_cvt_pk_bf16_f32 v159, v126, v127
	global_store_dwordx2 v237, v[158:159], s[96:97] offset:288
	s_add_u32 s2, s2, 0x4000
	s_addc_u32 s3, s3, 0
	s_add_u32 s96, s96, 0x2000
	s_addc_u32 s97, s97, 0
	global_store_dwordx4 v168, v[96:99], s[2:3] offset:0
	global_store_dwordx4 v168, v[100:103], s[2:3] offset:64
	global_store_dwordx4 v168, v[128:131], s[2:3] offset:512
	global_store_dwordx4 v168, v[132:135], s[2:3] offset:576
	v_cvt_pk_bf16_f32 v160, v96, v97
	v_cvt_pk_bf16_f32 v161, v98, v99
	global_store_dwordx2 v237, v[160:161], s[96:97] offset:0
	v_cvt_pk_bf16_f32 v162, v100, v101
	v_cvt_pk_bf16_f32 v163, v102, v103
	global_store_dwordx2 v237, v[162:163], s[96:97] offset:32
	v_cvt_pk_bf16_f32 v164, v128, v129
	v_cvt_pk_bf16_f32 v165, v130, v131
	global_store_dwordx2 v237, v[164:165], s[96:97] offset:256
; DI unsigned pk2(float lo, float hi) { const f32x2 v = {lo, hi}; return __builtin_bit_cast(unsigned, __builtin_convertvector(v, bf2_t)); }
; DI void gemm_in(const Params& p, int l, int bid, int nb, char* smem, const int tid) {
;     ...
;         if (seg == 0 || seg == 3) {
;             bf16_t* Q = (bf16_t*)(p.ws + (seg == 0 ? B_QA : B_QC));
; #pragma unroll
;             for (int mi = 0; mi < 4; ++mi) {
;                 const int row = m0 + wm * 64 + mi * 16 + r;
; #pragma unroll
;                 for (int ni = 0; ni < 4; ++ni) {
;                     u32x2 w; w.x = pk2(acc[mi][ni][0], acc[mi][ni][1]); w.y = pk2(acc[mi][ni][2], acc[mi][ni][3]);
;                     *(u32x2*)(Q + (size_t)row * 256 + cin + ni * 16 + q * 4) = w;
;                 }
;             }
;         } else if (seg < 6) {
;             const size_t boff = seg == 1 ? B_KA : seg == 2 ? B_VA : seg == 4 ? B_KC : B_VC;
;             const bool samp = m0 >= NP;
;             const size_t ooff = samp ? (seg == 1 ? O_AKS : seg == 2 ? O_AVS : seg == 4 ? O_CKS : O_CVS) : (seg == 1 ? O_AKP : seg == 2 ? O_AVP : seg == 4 ? O_CKP : O_CVP);
;             bf16_t* KV = (bf16_t*)(p.ws + boff);
; #pragma unroll
;             for (int mi = 0; mi < 4; ++mi) {
;                 const int row = m0 + wm * 64 + mi * 16 + r;
;                 const size_t srow = samp ? (size_t)(l * NS + (row - NP)) : (size_t)(l * NP + row);
;                 const size_t kr = (size_t)krow_of(row);
; #pragma unroll
;                 for (int ni = 0; ni < 4; ++ni) {
;                     const int c = cin + ni * 16 + q * 4;
;                     *(f32x4*)(p.out + ooff + srow * 256 + c) = acc[mi][ni];
;                     u32x2 w; w.x = pk2(acc[mi][ni][0], acc[mi][ni][1]); w.y = pk2(acc[mi][ni][2], acc[mi][ni][3]);
;                     *(u32x2*)(KV + kr * 256 + c) = w;
;                 }
;             }
	v_cvt_pk_bf16_f32 v166, v132, v133
	v_cvt_pk_bf16_f32 v167, v134, v135
	global_store_dwordx2 v237, v[166:167], s[96:97] offset:288
	s_add_u32 s2, s2, 0x4000
	s_addc_u32 s3, s3, 0
	s_add_u32 s96, s96, 0x2000
	s_addc_u32 s97, s97, 0
	global_store_dwordx4 v168, v[104:107], s[2:3] offset:0
	global_store_dwordx4 v168, v[108:111], s[2:3] offset:64
	global_store_dwordx4 v168, v[136:139], s[2:3] offset:512
	global_store_dwordx4 v168, v[140:143], s[2:3] offset:576
	v_cvt_pk_bf16_f32 v152, v104, v105
	v_cvt_pk_bf16_f32 v153, v106, v107
	global_store_dwordx2 v237, v[152:153], s[96:97] offset:0
	v_cvt_pk_bf16_f32 v154, v108, v109
	v_cvt_pk_bf16_f32 v155, v110, v111
	global_store_dwordx2 v237, v[154:155], s[96:97] offset:32
	v_cvt_pk_bf16_f32 v156, v136, v137
	v_cvt_pk_bf16_f32 v157, v138, v139
	global_store_dwordx2 v237, v[156:157], s[96:97] offset:256
	v_cvt_pk_bf16_f32 v158, v140, v141
	v_cvt_pk_bf16_f32 v159, v142, v143
	global_store_dwordx2 v237, v[158:159], s[96:97] offset:288
	s_add_u32 s2, s2, 0x4000
	s_addc_u32 s3, s3, 0
	s_add_u32 s96, s96, 0x2000
	s_addc_u32 s97, s97, 0
	global_store_dwordx4 v168, v[112:115], s[2:3] offset:0
	global_store_dwordx4 v168, v[116:119], s[2:3] offset:64
	global_store_dwordx4 v168, v[144:147], s[2:3] offset:512
	global_store_dwordx4 v168, v[148:151], s[2:3] offset:576
	v_cvt_pk_bf16_f32 v160, v112, v113
	v_cvt_pk_bf16_f32 v161, v114, v115
	global_store_dwordx2 v237, v[160:161], s[96:97] offset:0
	v_cvt_pk_bf16_f32 v162, v116, v117
	v_cvt_pk_bf16_f32 v163, v118, v119
	global_store_dwordx2 v237, v[162:163], s[96:97] offset:32
	v_cvt_pk_bf16_f32 v164, v144, v145
	v_cvt_pk_bf16_f32 v165, v146, v147
	global_store_dwordx2 v237, v[164:165], s[96:97] offset:256
	v_cvt_pk_bf16_f32 v166, v148, v149
	v_cvt_pk_bf16_f32 v167, v150, v151
	global_store_dwordx2 v237, v[166:167], s[96:97] offset:288
	s_branch .Lin_done1
.Lin_q1:
	s_mov_b32 s62, 0x5ae0000
	s_cmp_eq_u32 s58, 0
	s_cselect_b32 s62, 0x52c0000, s62
	s_lshl_b32 s37, s57, 17
	s_add_u32 s62, s62, s37
	s_add_u32 s96, s88, s62
	s_addc_u32 s97, s89, 0
	v_cvt_pk_bf16_f32 v152, v24, v25
	v_cvt_pk_bf16_f32 v153, v26, v27
	global_store_dwordx2 v237, v[152:153], s[96:97] offset:0
	v_cvt_pk_bf16_f32 v154, v28, v29
	v_cvt_pk_bf16_f32 v155, v30, v31
	global_store_dwordx2 v237, v[154:155], s[96:97] offset:32
	v_cvt_pk_bf16_f32 v156, v56, v57
	v_cvt_pk_bf16_f32 v157, v58, v59
	global_store_dwordx2 v237, v[156:157], s[96:97] offset:256
	v_cvt_pk_bf16_f32 v158, v60, v61
	v_cvt_pk_bf16_f32 v159, v62, v63
	global_store_dwordx2 v237, v[158:159], s[96:97] offset:288
	s_add_u32 s96, s96, 0x2000
	s_addc_u32 s97, s97, 0
	v_cvt_pk_bf16_f32 v160, v32, v33
	v_cvt_pk_bf16_f32 v161, v34, v35
	global_store_dwordx2 v237, v[160:161], s[96:97] offset:0
	v_cvt_pk_bf16_f32 v162, v36, v37
	v_cvt_pk_bf16_f32 v163, v38, v39
	global_store_dwordx2 v237, v[162:163], s[96:97] offset:32
	v_cvt_pk_bf16_f32 v164, v64, v65
	v_cvt_pk_bf16_f32 v165, v66, v67
	global_store_dwordx2 v237, v[164:165], s[96:97] offset:256
	v_cvt_pk_bf16_f32 v166, v68, v69
	v_cvt_pk_bf16_f32 v167, v70, v71
	global_store_dwordx2 v237, v[166:167], s[96:97] offset:288
	s_add_u32 s96, s96, 0x2000
	s_addc_u32 s97, s97, 0
	v_cvt_pk_bf16_f32 v152, v40, v41
	v_cvt_pk_bf16_f32 v153, v42, v43
	global_store_dwordx2 v237, v[152:153], s[96:97] offset:0
	v_cvt_pk_bf16_f32 v154, v44, v45
	v_cvt_pk_bf16_f32 v155, v46, v47
	global_store_dwordx2 v237, v[154:155], s[96:97] offset:32
	v_cvt_pk_bf16_f32 v156, v72, v73
	v_cvt_pk_bf16_f32 v157, v74, v75
	global_store_dwordx2 v237, v[156:157], s[96:97] offset:256
	v_cvt_pk_bf16_f32 v158, v76, v77
	v_cvt_pk_bf16_f32 v159, v78, v79
	global_store_dwordx2 v237, v[158:159], s[96:97] offset:288
	s_add_u32 s96, s96, 0x2000
	s_addc_u32 s97, s97, 0
	v_cvt_pk_bf16_f32 v160, v48, v49
	v_cvt_pk_bf16_f32 v161, v50, v51
	global_store_dwordx2 v237, v[160:161], s[96:97] offset:0
	v_cvt_pk_bf16_f32 v162, v52, v53
	v_cvt_pk_bf16_f32 v163, v54, v55
	global_store_dwordx2 v237, v[162:163], s[96:97] offset:32
	v_cvt_pk_bf16_f32 v164, v80, v81
	v_cvt_pk_bf16_f32 v165, v82, v83
	global_store_dwordx2 v237, v[164:165], s[96:97] offset:256
	v_cvt_pk_bf16_f32 v166, v84, v85
	v_cvt_pk_bf16_f32 v167, v86, v87
	global_store_dwordx2 v237, v[166:167], s[96:97] offset:288
	s_add_u32 s96, s96, 0xa000
	s_addc_u32 s97, s97, 0
	v_cvt_pk_bf16_f32 v152, v88, v89
	v_cvt_pk_bf16_f32 v153, v90, v91
	global_store_dwordx2 v237, v[152:153], s[96:97] offset:0
	v_cvt_pk_bf16_f32 v154, v92, v93
	v_cvt_pk_bf16_f32 v155, v94, v95
	global_store_dwordx2 v237, v[154:155], s[96:97] offset:32
	v_cvt_pk_bf16_f32 v156, v120, v121
	v_cvt_pk_bf16_f32 v157, v122, v123
	global_store_dwordx2 v237, v[156:157], s[96:97] offset:256
	v_cvt_pk_bf16_f32 v158, v124, v125
	v_cvt_pk_bf16_f32 v159, v126, v127
	global_store_dwordx2 v237, v[158:159], s[96:97] offset:288
	s_add_u32 s96, s96, 0x2000
	s_addc_u32 s97, s97, 0
	v_cvt_pk_bf16_f32 v160, v96, v97
	v_cvt_pk_bf16_f32 v161, v98, v99
	global_store_dwordx2 v237, v[160:161], s[96:97] offset:0
	v_cvt_pk_bf16_f32 v162, v100, v101
	v_cvt_pk_bf16_f32 v163, v102, v103
	global_store_dwordx2 v237, v[162:163], s[96:97] offset:32
	v_cvt_pk_bf16_f32 v164, v128, v129
	v_cvt_pk_bf16_f32 v165, v130, v131
	global_store_dwordx2 v237, v[164:165], s[96:97] offset:256
	v_cvt_pk_bf16_f32 v166, v132, v133
	v_cvt_pk_bf16_f32 v167, v134, v135
	global_store_dwordx2 v237, v[166:167], s[96:97] offset:288
	s_add_u32 s96, s96, 0x2000
	s_addc_u32 s97, s97, 0
	v_cvt_pk_bf16_f32 v152, v104, v105
	v_cvt_pk_bf16_f32 v153, v106, v107
	global_store_dwordx2 v237, v[152:153], s[96:97] offset:0
	v_cvt_pk_bf16_f32 v154, v108, v109
	v_cvt_pk_bf16_f32 v155, v110, v111
	global_store_dwordx2 v237, v[154:155], s[96:97] offset:32
	v_cvt_pk_bf16_f32 v156, v136, v137
	v_cvt_pk_bf16_f32 v157, v138, v139
	global_store_dwordx2 v237, v[156:157], s[96:97] offset:256
	v_cvt_pk_bf16_f32 v158, v140, v141
	v_cvt_pk_bf16_f32 v159, v142, v143
	global_store_dwordx2 v237, v[158:159], s[96:97] offset:288
	s_add_u32 s96, s96, 0x2000
	s_addc_u32 s97, s97, 0
	v_cvt_pk_bf16_f32 v160, v112, v113
	v_cvt_pk_bf16_f32 v161, v114, v115
	global_store_dwordx2 v237, v[160:161], s[96:97] offset:0
	v_cvt_pk_bf16_f32 v162, v116, v117
	v_cvt_pk_bf16_f32 v163, v118, v119
	global_store_dwordx2 v237, v[162:163], s[96:97] offset:32
	v_cvt_pk_bf16_f32 v164, v144, v145
	v_cvt_pk_bf16_f32 v165, v146, v147
	global_store_dwordx2 v237, v[164:165], s[96:97] offset:256
	v_cvt_pk_bf16_f32 v166, v148, v149
	v_cvt_pk_bf16_f32 v167, v150, v151
	global_store_dwordx2 v237, v[166:167], s[96:97] offset:288
	s_branch .Lin_done1
; DI void gemm_in(const Params& p, int l, int bid, int nb, char* smem, const int tid) {
;     ...
;     for (; have; tm = tm2, tn = tn2) {
;         have = ti.next(tm2, tn2);
;     ...
;         } else {
;             float* SM = (float*)(p.ws + B_SMALL);
; #pragma unroll
;             for (int mi = 0; mi < 4; ++mi) {
;                 const int row = m0 + wm * 64 + mi * 16 + r;
; #pragma unroll
;                 for (int ni = 0; ni < 4; ++ni) *(f32x4*)(SM + (size_t)row * 512 + (nb0 - 1536) + ni * 16 + q * 4) = acc[mi][ni];
;             }
;         }
.Lin_sm1:
	s_sub_u32 s1, s58, 6
	s_lshl_b32 s1, s1, 10
	s_lshl_b32 s37, s57, 19
	s_add_u32 s1, s1, s37
	s_add_u32 s1, s1, 0xac20000
	s_add_u32 s2, s88, s1
	s_addc_u32 s3, s89, 0
	v_lshl_add_u32 v168, v230, 11, v236
	global_store_dwordx4 v168, v[24:27], s[2:3] offset:0
	global_store_dwordx4 v168, v[28:31], s[2:3] offset:64
	global_store_dwordx4 v168, v[56:59], s[2:3] offset:512
	global_store_dwordx4 v168, v[60:63], s[2:3] offset:576
	s_add_u32 s2, s2, 0x8000
	s_addc_u32 s3, s3, 0
	global_store_dwordx4 v168, v[32:35], s[2:3] offset:0
	global_store_dwordx4 v168, v[36:39], s[2:3] offset:64
	global_store_dwordx4 v168, v[64:67], s[2:3] offset:512
	global_store_dwordx4 v168, v[68:71], s[2:3] offset:576
	s_add_u32 s2, s2, 0x8000
	s_addc_u32 s3, s3, 0
	global_store_dwordx4 v168, v[40:43], s[2:3] offset:0
	global_store_dwordx4 v168, v[44:47], s[2:3] offset:64
	global_store_dwordx4 v168, v[72:75], s[2:3] offset:512
	global_store_dwordx4 v168, v[76:79], s[2:3] offset:576
	s_add_u32 s2, s2, 0x8000
	s_addc_u32 s3, s3, 0
	global_store_dwordx4 v168, v[48:51], s[2:3] offset:0
	global_store_dwordx4 v168, v[52:55], s[2:3] offset:64
	global_store_dwordx4 v168, v[80:83], s[2:3] offset:512
	global_store_dwordx4 v168, v[84:87], s[2:3] offset:576
	s_add_u32 s2, s2, 0x28000
	s_addc_u32 s3, s3, 0
	global_store_dwordx4 v168, v[88:91], s[2:3] offset:0
	global_store_dwordx4 v168, v[92:95], s[2:3] offset:64
	global_store_dwordx4 v168, v[120:123], s[2:3] offset:512
	global_store_dwordx4 v168, v[124:127], s[2:3] offset:576
	s_add_u32 s2, s2, 0x8000
	s_addc_u32 s3, s3, 0
	global_store_dwordx4 v168, v[96:99], s[2:3] offset:0
	global_store_dwordx4 v168, v[100:103], s[2:3] offset:64
	global_store_dwordx4 v168, v[128:131], s[2:3] offset:512
	global_store_dwordx4 v168, v[132:135], s[2:3] offset:576
	s_add_u32 s2, s2, 0x8000
	s_addc_u32 s3, s3, 0
	global_store_dwordx4 v168, v[104:107], s[2:3] offset:0
	global_store_dwordx4 v168, v[108:111], s[2:3] offset:64
	global_store_dwordx4 v168, v[136:139], s[2:3] offset:512
	global_store_dwordx4 v168, v[140:143], s[2:3] offset:576
	s_add_u32 s2, s2, 0x8000
	s_addc_u32 s3, s3, 0
	global_store_dwordx4 v168, v[112:115], s[2:3] offset:0
	global_store_dwordx4 v168, v[116:119], s[2:3] offset:64
	global_store_dwordx4 v168, v[144:147], s[2:3] offset:512
	global_store_dwordx4 v168, v[148:151], s[2:3] offset:576
.Lin_done1:
	s_nop 1
	s_cmp_eq_u32 s54, 0
	s_cbranch_scc1 .Lin_stub
	s_mov_b32 s51, s76
	s_mov_b32 s57, s59
	s_mov_b32 s58, s60
	s_branch .Lin_tile
.Lin_stub:
	s_waitcnt vmcnt(0) lgkmcnt(0)
	s_barrier
	v_mov_b32_e32 v227, v193
	v_readlane_b32 s3, v231, 0
	v_readlane_b32 s0, v238, 54
	s_add_i32 s3, s3, 0x400
	v_readfirstlane_b32 s33, v227
	s_movk_i32 s2, 0x410
	s_mov_b32 s10, s0
	s_branch .Lin_old661
